# RG-LRU: conv taps/bias loaded once per unit (first tile) into live registers instead of every tile
# speedup vs baseline: 1.0028x; 1.0028x over previous
.LBB0_256:
	s_waitcnt lgkmcnt(0)
	s_barrier
	s_cmp_lg_u32 s34, 0
	s_cbranch_scc1 .Llruw_skip_p
	global_load_dwordx4 v[172:175], v[76:77], off offset:16
	global_load_dwordx4 v[184:187], v[76:77], off
	global_load_dwordx4 v[190:193], v[80:81], off offset:16
	global_load_dwordx4 v[194:197], v[80:81], off
	global_load_dwordx4 v[198:201], v[82:83], off offset:16
	global_load_dwordx4 v[208:211], v[82:83], off
	global_load_dwordx4 v[212:215], v[84:85], off offset:16
	global_load_dwordx4 v[216:219], v[84:85], off
	global_load_dwordx4 v[220:223], v[86:87], off offset:16
	global_load_dwordx4 v[224:227], v[86:87], off
	s_waitcnt vmcnt(0)
.Llruw_skip_p:
	s_waitcnt vmcnt(2)
	v_lshlrev_b32_e32 v2, 16, v4
	v_and_b32_e32 v3, 0xffff0000, v4
	v_lshlrev_b32_e32 v140, 16, v8
	v_and_b32_e32 v141, 0xffff0000, v8
	v_lshlrev_b32_e32 v142, 16, v9
	v_and_b32_e32 v143, 0xffff0000, v9
	v_lshlrev_b32_e32 v144, 16, v10
	v_and_b32_e32 v145, 0xffff0000, v10
	v_lshlrev_b32_e32 v146, 16, v11
	v_and_b32_e32 v147, 0xffff0000, v11
	s_add_i32 s22, s34, 1
	s_cmp_gt_u32 s34, 2

	v_pk_fma_f32 v[2:3], v[194:195], v[2:3], v[184:185]

	v_pk_fma_f32 v[2:3], v[208:209], v[140:141], v[2:3]
	v_lshlrev_b32_e32 v140, 16, v12
	v_and_b32_e32 v141, 0xffff0000, v12

	v_pk_fma_f32 v[2:3], v[216:217], v[140:141], v[2:3]
	v_lshlrev_b32_e32 v140, 16, v16
	v_and_b32_e32 v141, 0xffff0000, v16

	v_pk_fma_f32 v[2:3], v[224:225], v[140:141], v[2:3]
	v_lshlrev_b32_e32 v140, 16, v5
	v_and_b32_e32 v141, 0xffff0000, v5
	v_pk_fma_f32 v[140:141], v[196:197], v[140:141], v[186:187]
	s_nop 0
	v_pk_fma_f32 v[140:141], v[210:211], v[142:143], v[140:141]
	v_lshlrev_b32_e32 v142, 16, v13
	v_and_b32_e32 v143, 0xffff0000, v13
	v_pk_fma_f32 v[140:141], v[218:219], v[142:143], v[140:141]
	v_lshlrev_b32_e32 v142, 16, v17
	v_and_b32_e32 v143, 0xffff0000, v17
	v_pk_fma_f32 v[142:143], v[226:227], v[142:143], v[140:141]
	v_lshlrev_b32_e32 v140, 16, v6
	v_and_b32_e32 v141, 0xffff0000, v6
	v_pk_fma_f32 v[140:141], v[190:191], v[140:141], v[172:173]
	s_nop 0
	v_pk_fma_f32 v[140:141], v[198:199], v[144:145], v[140:141]
	v_lshlrev_b32_e32 v144, 16, v14
	v_and_b32_e32 v145, 0xffff0000, v14
	v_pk_fma_f32 v[140:141], v[212:213], v[144:145], v[140:141]
	v_lshlrev_b32_e32 v144, 16, v18
	v_and_b32_e32 v145, 0xffff0000, v18
	v_pk_fma_f32 v[144:145], v[220:221], v[144:145], v[140:141]
	v_lshlrev_b32_e32 v140, 16, v7
	v_and_b32_e32 v141, 0xffff0000, v7
	v_pk_fma_f32 v[140:141], v[192:193], v[140:141], v[174:175]
	s_nop 0
	v_pk_fma_f32 v[140:141], v[200:201], v[146:147], v[140:141]
	v_lshlrev_b32_e32 v146, 16, v15
	v_and_b32_e32 v147, 0xffff0000, v15
	v_pk_fma_f32 v[140:141], v[214:215], v[146:147], v[140:141]
	v_lshlrev_b32_e32 v146, 16, v19
	v_and_b32_e32 v147, 0xffff0000, v19
	v_pk_fma_f32 v[146:147], v[222:223], v[146:147], v[140:141]
	v_cvt_pk_bf16_f32 v140, v2, v3
	v_lshlrev_b32_e32 v2, 16, v20
	v_and_b32_e32 v3, 0xffff0000, v20
	v_pk_fma_f32 v[2:3], v[194:195], v[2:3], v[184:185]
	v_lshlrev_b32_e32 v60, 16, v24
	v_and_b32_e32 v61, 0xffff0000, v24
	v_pk_fma_f32 v[2:3], v[208:209], v[60:61], v[2:3]
	v_lshlrev_b32_e32 v60, 16, v28
	v_and_b32_e32 v61, 0xffff0000, v28
	v_pk_fma_f32 v[2:3], v[216:217], v[60:61], v[2:3]
	v_lshlrev_b32_e32 v60, 16, v32
	v_and_b32_e32 v61, 0xffff0000, v32
	v_pk_fma_f32 v[2:3], v[224:225], v[60:61], v[2:3]
	v_lshlrev_b32_e32 v56, 16, v21
	v_and_b32_e32 v57, 0xffff0000, v21
	v_pk_fma_f32 v[56:57], v[196:197], v[56:57], v[186:187]
	v_lshlrev_b32_e32 v60, 16, v25
	v_and_b32_e32 v61, 0xffff0000, v25
	v_pk_fma_f32 v[56:57], v[210:211], v[60:61], v[56:57]
	v_lshlrev_b32_e32 v60, 16, v29
	v_and_b32_e32 v61, 0xffff0000, v29
	v_pk_fma_f32 v[56:57], v[218:219], v[60:61], v[56:57]
	v_lshlrev_b32_e32 v60, 16, v33
	v_and_b32_e32 v61, 0xffff0000, v33
	v_pk_fma_f32 v[56:57], v[226:227], v[60:61], v[56:57]
	v_lshlrev_b32_e32 v58, 16, v22
	v_and_b32_e32 v59, 0xffff0000, v22
	v_pk_fma_f32 v[36:37], v[190:191], v[58:59], v[172:173]
	v_lshlrev_b32_e32 v40, 16, v26
	v_and_b32_e32 v41, 0xffff0000, v26
	v_pk_fma_f32 v[36:37], v[198:199], v[40:41], v[36:37]
	v_lshlrev_b32_e32 v40, 16, v30
	v_and_b32_e32 v41, 0xffff0000, v30
	v_pk_fma_f32 v[36:37], v[212:213], v[40:41], v[36:37]
	v_lshlrev_b32_e32 v40, 16, v34
	v_and_b32_e32 v41, 0xffff0000, v34
	v_pk_fma_f32 v[40:41], v[220:221], v[40:41], v[36:37]
	v_lshlrev_b32_e32 v36, 16, v23
	v_and_b32_e32 v37, 0xffff0000, v23
	v_pk_fma_f32 v[36:37], v[192:193], v[36:37], v[174:175]
	v_lshlrev_b32_e32 v38, 16, v27
	v_and_b32_e32 v39, 0xffff0000, v27
	v_pk_fma_f32 v[36:37], v[200:201], v[38:39], v[36:37]
	v_lshlrev_b32_e32 v38, 16, v31
	v_and_b32_e32 v39, 0xffff0000, v31
	v_pk_fma_f32 v[36:37], v[214:215], v[38:39], v[36:37]
	v_lshlrev_b32_e32 v38, 16, v35
	v_and_b32_e32 v39, 0xffff0000, v35
	v_pk_fma_f32 v[42:43], v[222:223], v[38:39], v[36:37]
	v_cvt_pk_bf16_f32 v141, v142, v143
	v_cvt_pk_bf16_f32 v142, v144, v145
	v_cvt_pk_bf16_f32 v143, v146, v147
	v_cvt_pk_bf16_f32 v36, v2, v3
	v_cvt_pk_bf16_f32 v37, v56, v57
	v_cvt_pk_bf16_f32 v38, v40, v41
	v_cvt_pk_bf16_f32 v39, v42, v43
	ds_write_b128 v94, v[140:143]
	ds_write_b128 v96, v[36:39]
	s_cbranch_scc1 .LBB0_270
	s_sub_i32 s20, 2, s34
	s_and_b64 s[18:19], s[16:17], exec
	s_cselect_b32 s18, s22, s20
	s_lshl_b32 s18, s18, 6
	s_add_i32 s19, s18, -2
	v_mov_b32_e32 v8, v0
	v_mov_b32_e32 v9, v0
	v_add_u32_e32 v1, s19, v93
	v_mov_b32_e32 v10, v0
	v_mov_b32_e32 v11, v0
	v_mov_b64_e32 v[4:5], v[8:9]
	v_cmp_gt_u32_e32 vcc, s33, v1
	v_mov_b64_e32 v[6:7], v[10:11]
	s_and_saveexec_b64 s[20:21], vcc
	s_cbranch_execz .LBB0_259
	v_or_b32_e32 v2, s50, v1
	v_mov_b32_e32 v3, v0
	v_lshlrev_b64 v[2:3], 12, v[2:3]
	v_lshl_add_u64 v[2:3], v[88:89], 0, v[2:3]
	global_load_dwordx4 v[4:7], v[2:3], off offset:2048

.LBB0_291:
	s_waitcnt lgkmcnt(0)
	s_barrier
	s_cmp_lg_u32 s20, 0
	s_cbranch_scc1 .Llruw_skip_s
	global_load_dwordx4 v[172:175], v[76:77], off offset:16
	global_load_dwordx4 v[184:187], v[76:77], off
	global_load_dwordx4 v[190:193], v[80:81], off offset:16
	global_load_dwordx4 v[194:197], v[80:81], off
	global_load_dwordx4 v[198:201], v[82:83], off offset:16
	global_load_dwordx4 v[208:211], v[82:83], off
	global_load_dwordx4 v[212:215], v[84:85], off offset:16
	global_load_dwordx4 v[216:219], v[84:85], off
	global_load_dwordx4 v[220:223], v[86:87], off offset:16
	global_load_dwordx4 v[224:227], v[86:87], off
	s_waitcnt vmcnt(0)
.Llruw_skip_s:
	s_waitcnt vmcnt(2)
	v_lshlrev_b32_e32 v2, 16, v4
	v_and_b32_e32 v3, 0xffff0000, v4
	v_lshlrev_b32_e32 v140, 16, v8
	v_and_b32_e32 v141, 0xffff0000, v8
	v_lshlrev_b32_e32 v142, 16, v9
	v_and_b32_e32 v143, 0xffff0000, v9
	v_lshlrev_b32_e32 v144, 16, v10
	v_and_b32_e32 v145, 0xffff0000, v10
	v_lshlrev_b32_e32 v146, 16, v11
	v_and_b32_e32 v147, 0xffff0000, v11
	s_add_i32 s14, s20, 1
	s_cmp_gt_u32 s20, 14

	v_pk_fma_f32 v[2:3], v[194:195], v[2:3], v[184:185]

	v_pk_fma_f32 v[2:3], v[208:209], v[140:141], v[2:3]
	v_lshlrev_b32_e32 v140, 16, v12
	v_and_b32_e32 v141, 0xffff0000, v12

	v_pk_fma_f32 v[2:3], v[216:217], v[140:141], v[2:3]
	v_lshlrev_b32_e32 v140, 16, v16
	v_and_b32_e32 v141, 0xffff0000, v16

	v_pk_fma_f32 v[2:3], v[224:225], v[140:141], v[2:3]
	v_lshlrev_b32_e32 v140, 16, v5
	v_and_b32_e32 v141, 0xffff0000, v5
	v_pk_fma_f32 v[140:141], v[196:197], v[140:141], v[186:187]
	s_nop 0
	v_pk_fma_f32 v[140:141], v[210:211], v[142:143], v[140:141]
	v_lshlrev_b32_e32 v142, 16, v13
	v_and_b32_e32 v143, 0xffff0000, v13
	v_pk_fma_f32 v[140:141], v[218:219], v[142:143], v[140:141]
	v_lshlrev_b32_e32 v142, 16, v17
	v_and_b32_e32 v143, 0xffff0000, v17
	v_pk_fma_f32 v[142:143], v[226:227], v[142:143], v[140:141]
	v_lshlrev_b32_e32 v140, 16, v6
	v_and_b32_e32 v141, 0xffff0000, v6
	v_pk_fma_f32 v[140:141], v[190:191], v[140:141], v[172:173]
	s_nop 0
	v_pk_fma_f32 v[140:141], v[198:199], v[144:145], v[140:141]
	v_lshlrev_b32_e32 v144, 16, v14
	v_and_b32_e32 v145, 0xffff0000, v14
	v_pk_fma_f32 v[140:141], v[212:213], v[144:145], v[140:141]
	v_lshlrev_b32_e32 v144, 16, v18
	v_and_b32_e32 v145, 0xffff0000, v18
	v_pk_fma_f32 v[144:145], v[220:221], v[144:145], v[140:141]
	v_lshlrev_b32_e32 v140, 16, v7
	v_and_b32_e32 v141, 0xffff0000, v7
	v_pk_fma_f32 v[140:141], v[192:193], v[140:141], v[174:175]
	s_nop 0
	v_pk_fma_f32 v[140:141], v[200:201], v[146:147], v[140:141]
	v_lshlrev_b32_e32 v146, 16, v15
	v_and_b32_e32 v147, 0xffff0000, v15
	v_pk_fma_f32 v[140:141], v[214:215], v[146:147], v[140:141]
	v_lshlrev_b32_e32 v146, 16, v19
	v_and_b32_e32 v147, 0xffff0000, v19
	v_pk_fma_f32 v[146:147], v[222:223], v[146:147], v[140:141]
	v_cvt_pk_bf16_f32 v140, v2, v3
	v_lshlrev_b32_e32 v2, 16, v20
	v_and_b32_e32 v3, 0xffff0000, v20
	v_pk_fma_f32 v[2:3], v[194:195], v[2:3], v[184:185]
	v_lshlrev_b32_e32 v60, 16, v24
	v_and_b32_e32 v61, 0xffff0000, v24
	v_pk_fma_f32 v[2:3], v[208:209], v[60:61], v[2:3]
	v_lshlrev_b32_e32 v60, 16, v28
	v_and_b32_e32 v61, 0xffff0000, v28
	v_pk_fma_f32 v[2:3], v[216:217], v[60:61], v[2:3]
	v_lshlrev_b32_e32 v60, 16, v32
	v_and_b32_e32 v61, 0xffff0000, v32
	v_pk_fma_f32 v[2:3], v[224:225], v[60:61], v[2:3]
	v_lshlrev_b32_e32 v56, 16, v21
	v_and_b32_e32 v57, 0xffff0000, v21
	v_pk_fma_f32 v[56:57], v[196:197], v[56:57], v[186:187]
	v_lshlrev_b32_e32 v60, 16, v25
	v_and_b32_e32 v61, 0xffff0000, v25
	v_pk_fma_f32 v[56:57], v[210:211], v[60:61], v[56:57]
	v_lshlrev_b32_e32 v60, 16, v29
	v_and_b32_e32 v61, 0xffff0000, v29
	v_pk_fma_f32 v[56:57], v[218:219], v[60:61], v[56:57]
	v_lshlrev_b32_e32 v60, 16, v33
	v_and_b32_e32 v61, 0xffff0000, v33
	v_pk_fma_f32 v[56:57], v[226:227], v[60:61], v[56:57]
	v_lshlrev_b32_e32 v58, 16, v22
	v_and_b32_e32 v59, 0xffff0000, v22
	v_pk_fma_f32 v[36:37], v[190:191], v[58:59], v[172:173]
	v_lshlrev_b32_e32 v40, 16, v26
	v_and_b32_e32 v41, 0xffff0000, v26
	v_pk_fma_f32 v[36:37], v[198:199], v[40:41], v[36:37]
	v_lshlrev_b32_e32 v40, 16, v30
	v_and_b32_e32 v41, 0xffff0000, v30
	v_pk_fma_f32 v[36:37], v[212:213], v[40:41], v[36:37]
	v_lshlrev_b32_e32 v40, 16, v34
	v_and_b32_e32 v41, 0xffff0000, v34
	v_pk_fma_f32 v[40:41], v[220:221], v[40:41], v[36:37]
	v_lshlrev_b32_e32 v36, 16, v23
	v_and_b32_e32 v37, 0xffff0000, v23
	v_pk_fma_f32 v[36:37], v[192:193], v[36:37], v[174:175]
	v_lshlrev_b32_e32 v38, 16, v27
	v_and_b32_e32 v39, 0xffff0000, v27
	v_pk_fma_f32 v[36:37], v[200:201], v[38:39], v[36:37]
	v_lshlrev_b32_e32 v38, 16, v31
	v_and_b32_e32 v39, 0xffff0000, v31
	v_pk_fma_f32 v[36:37], v[214:215], v[38:39], v[36:37]
	v_lshlrev_b32_e32 v38, 16, v35
	v_and_b32_e32 v39, 0xffff0000, v35
	v_pk_fma_f32 v[42:43], v[222:223], v[38:39], v[36:37]
	v_cvt_pk_bf16_f32 v141, v142, v143
	v_cvt_pk_bf16_f32 v142, v144, v145
	v_cvt_pk_bf16_f32 v143, v146, v147
	v_cvt_pk_bf16_f32 v36, v2, v3
	v_cvt_pk_bf16_f32 v37, v56, v57
	v_cvt_pk_bf16_f32 v38, v40, v41
	v_cvt_pk_bf16_f32 v39, v42, v43
	ds_write_b128 v94, v[140:143]
	ds_write_b128 v96, v[36:39]
	s_cbranch_scc1 .LBB0_305
	s_sub_i32 s15, 14, s20
	s_and_b64 s[4:5], s[12:13], exec
	s_cselect_b32 s4, s14, s15
	s_lshl_b32 s15, s4, 6
	s_add_i32 s16, s15, -2
	v_mov_b32_e32 v8, v0
	v_mov_b32_e32 v9, v0
	v_add_u32_e32 v1, s16, v93
	v_mov_b32_e32 v10, v0
	v_mov_b32_e32 v11, v0
	v_mov_b64_e32 v[4:5], v[8:9]
	v_cmp_gt_u32_e32 vcc, s89, v1
	v_mov_b64_e32 v[6:7], v[10:11]
	s_and_saveexec_b64 s[4:5], vcc
	s_cbranch_execz .LBB0_294
	v_or_b32_e32 v2, s34, v1
	v_ashrrev_i32_e32 v3, 31, v2
	v_lshlrev_b64 v[2:3], 12, v[2:3]
	v_lshl_add_u64 v[2:3], v[88:89], 0, v[2:3]
	global_load_dwordx4 v[4:7], v[2:3], off offset:2048
